# scan loader waves: 4 register sets (records requested 3 steps ahead), LDS writes via ds_write_b64 + per-parity bases
# baseline (speedup 1.0000x reference)
; __device__ __forceinline__ void scan_bh(LAS unsigned char* lds, const ScanP& P, int b, int h, int half, int tid, int lane, int wave) {
;     ...
;     if (!cw) {
;         const int lt = tid - 256, wrow = lt >> 4, wc16 = lt & 15, arow = lt >> 3, ac16 = lt & 7;
;         const int wperm = (wc16 >> 2) * 32 + ((((wc16 & 3) * 8) & 15) >> 2) * 8 + (((wc16 & 3) * 8) >> 4) * 4, aperm = (ac16 >> 2) * 32 + ((((ac16 & 3) * 8) & 15) >> 2) * 8 + (((ac16 & 3) * 8) >> 4) * 4;
;         const unsigned oW = (unsigned)TR_W + (unsigned)(wrow * 128 + wc16 * 8) * 2u, oQ = oW + (unsigned)(TR_Q - TR_W), oA = (unsigned)TR_A + (unsigned)(arow * 64 + ac16 * 8) * 2u, oK = oA + (unsigned)(TR_K - TR_A);
;         const unsigned lW = (unsigned)(wrow * PS + wperm) * 2u, lA = (unsigned)(arow * TS + aperm) * 2u;
;         u32x4 sa[14], sb[14];
;     ...
;         L_LOAD(0, sa); L_STORE(lds, sa); L_LOAD(1, sa);
;         __syncthreads();
.LBB0_514:
	s_and_b64 vcc, exec, s[4:5]
	s_mov_b32 s54, s13
	s_mov_b64 s[20:21], 0x28e00000
	s_cbranch_vccz .LBB0_534
	s_mov_b32 s4, -1
	s_mov_b32 s10, s2
	s_waitcnt vmcnt(0)
	v_mbcnt_lo_u32_b32 v0, s4, 0
	v_mbcnt_hi_u32_b32 v0, s4, v0
	v_or_b32_e32 v145, s3, v0
	s_mov_b64 s[4:5], s[0:1]
	s_and_b32 s8, s10, 7
	v_mov_b64_e32 v[0:1], s[4:5]
	s_waitcnt lgkmcnt(0)
	flat_load_dwordx4 v[0:3], v[0:1] offset:144
	v_readfirstlane_b32 s4, v145
	s_ashr_i32 s9, s10, 4
	s_ashr_i32 s11, s4, 6
	s_mov_b64 s[4:5], 0x22400000
	v_and_b32_e32 v144, 15, v145
	s_cmp_gt_i32 s11, 3
	s_waitcnt vmcnt(0) lgkmcnt(0)
	v_lshl_add_u64 v[116:117], v[2:3], 0, s[4:5]
	s_mov_b64 s[4:5], -1
	s_cbranch_scc0 .LBB0_525
	v_add_u32_e32 v4, 0xffffff00, v145
	v_ashrrev_i32_e32 v147, 4, v4
	v_ashrrev_i32_e32 v150, 3, v4
	v_lshlrev_b32_e32 v146, 3, v144
	v_lshlrev_b32_e32 v148, 1, v145
	v_and_b32_e32 v151, 0x60, v146
	v_lshlrev_b32_e32 v146, 4, v145
	v_and_b32_e32 v148, 4, v148
	v_lshlrev_b32_e32 v149, 3, v145
	v_and_or_b32 v146, v146, 16, v148
	v_and_b32_e32 v156, 32, v149
	v_mad_u64_u32 v[148:149], s[4:5], v147, s50, v[146:147]
	s_movk_i32 s4, 0x48
	s_nop 0
	v_mad_u64_u32 v[146:147], s[4:5], v150, s4, v[146:147]
	v_add_lshl_u32 v160, v148, v151, 1
	v_add_u32_e32 v147, 0, v160
	v_add_lshl_u32 v146, v146, v156, 1
	v_mov_b32_e32 v247, v160
	v_add_u32_e32 v248, 0xf400, v160
	v_mov_b32_e32 v249, v146
	v_add_u32_e32 v250, 0xf400, v146
	v_lshlrev_b32_e32 v5, 4, v4
	v_add_u32_e32 v240, 0x1000, v5
	v_add_u32_e32 v241, 0x3000, v5
	v_add_u32_e32 v242, 0x5000, v5
	v_add_u32_e32 v243, 0x7000, v5
	v_add_u32_e32 v244, 0x9000, v5
	v_add_u32_e32 v245, 0xb000, v5
	v_add_u32_e32 v246, 0xd000, v5
	v_readfirstlane_b32 s6, v116
	v_readfirstlane_b32 s7, v117
	s_lshl_b32 s18, s9, 8
	s_or_b32 s18, s18, s8
	s_mul_hi_u32 s15, s18, 0x1a000
	s_mul_i32 s14, s18, 0x1a000
	s_add_u32 s14, s14, s6
	s_addc_u32 s15, s15, s7
	s_mov_b32 s16, 0
	global_load_dwordx4 v[0:3], v240, s[14:15] offset:-4096
	global_load_dwordx4 v[4:7], v240, s[14:15]
	global_load_dwordx4 v[8:11], v241, s[14:15] offset:-4096
	global_load_dwordx4 v[12:15], v241, s[14:15]
	global_load_dwordx4 v[16:19], v242, s[14:15] offset:-4096
	global_load_dwordx4 v[20:23], v242, s[14:15]
	global_load_dwordx4 v[24:27], v243, s[14:15] offset:-4096
	global_load_dwordx4 v[28:31], v243, s[14:15]
	global_load_dwordx4 v[32:35], v244, s[14:15] offset:-4096
	global_load_dwordx4 v[36:39], v244, s[14:15]
	global_load_dwordx4 v[40:43], v245, s[14:15] offset:-4096
	global_load_dwordx4 v[44:47], v245, s[14:15]
	global_load_dwordx4 v[48:51], v246, s[14:15] offset:-4096
	global_load_dwordx4 v[52:55], v246, s[14:15]
	s_add_u32 s14, s14, 0xd0000
	s_addc_u32 s15, s15, 0
	global_load_dwordx4 v[56:59], v240, s[14:15] offset:-4096
	global_load_dwordx4 v[60:63], v240, s[14:15]
	global_load_dwordx4 v[64:67], v241, s[14:15] offset:-4096
	global_load_dwordx4 v[68:71], v241, s[14:15]
	global_load_dwordx4 v[72:75], v242, s[14:15] offset:-4096
	global_load_dwordx4 v[76:79], v242, s[14:15]
	global_load_dwordx4 v[80:83], v243, s[14:15] offset:-4096
	global_load_dwordx4 v[84:87], v243, s[14:15]
	global_load_dwordx4 v[88:91], v244, s[14:15] offset:-4096
	global_load_dwordx4 v[92:95], v244, s[14:15]
	global_load_dwordx4 v[96:99], v245, s[14:15] offset:-4096
	global_load_dwordx4 v[100:103], v245, s[14:15]
	global_load_dwordx4 v[104:107], v246, s[14:15] offset:-4096
	global_load_dwordx4 v[108:111], v246, s[14:15]
	s_add_u32 s14, s14, 0xd0000
	s_addc_u32 s15, s15, 0
	global_load_dwordx4 v[112:115], v240, s[14:15] offset:-4096
	global_load_dwordx4 v[116:119], v240, s[14:15]
	global_load_dwordx4 v[120:123], v241, s[14:15] offset:-4096
	global_load_dwordx4 v[124:127], v241, s[14:15]
	global_load_dwordx4 v[128:131], v242, s[14:15] offset:-4096
	global_load_dwordx4 v[132:135], v242, s[14:15]
	global_load_dwordx4 v[136:139], v243, s[14:15] offset:-4096
	global_load_dwordx4 v[140:143], v243, s[14:15]
	global_load_dwordx4 v[144:147], v244, s[14:15] offset:-4096
	global_load_dwordx4 v[148:151], v244, s[14:15]
	global_load_dwordx4 v[156:159], v245, s[14:15] offset:-4096
	global_load_dwordx4 v[160:163], v245, s[14:15]
	global_load_dwordx4 v[164:167], v246, s[14:15] offset:-4096
	global_load_dwordx4 v[168:171], v246, s[14:15]
	s_add_u32 s14, s14, 0xd0000
	s_addc_u32 s15, s15, 0
	global_load_dwordx4 v[172:175], v240, s[14:15] offset:-4096
	global_load_dwordx4 v[176:179], v240, s[14:15]
	global_load_dwordx4 v[180:183], v241, s[14:15] offset:-4096
	global_load_dwordx4 v[184:187], v241, s[14:15]
	global_load_dwordx4 v[188:191], v242, s[14:15] offset:-4096
	global_load_dwordx4 v[200:203], v242, s[14:15]
	global_load_dwordx4 v[204:207], v243, s[14:15] offset:-4096
	global_load_dwordx4 v[208:211], v243, s[14:15]
	global_load_dwordx4 v[212:215], v244, s[14:15] offset:-4096
	global_load_dwordx4 v[216:219], v244, s[14:15]
	global_load_dwordx4 v[220:223], v245, s[14:15] offset:-4096
	global_load_dwordx4 v[224:227], v245, s[14:15]
	global_load_dwordx4 v[228:231], v246, s[14:15] offset:-4096
	global_load_dwordx4 v[232:235], v246, s[14:15]
	s_add_u32 s14, s14, 0xd0000
	s_addc_u32 s15, s15, 0
	s_waitcnt vmcnt(55)
	ds_write_b64 v247, v[0:1]
	ds_write_b64 v247, v[2:3] offset:16
	s_waitcnt vmcnt(54)
	ds_write_b64 v247, v[4:5] offset:4352
	ds_write_b64 v247, v[6:7] offset:4368
	s_waitcnt vmcnt(53)
	ds_write_b64 v247, v[8:9] offset:8704
	ds_write_b64 v247, v[10:11] offset:8720
	s_waitcnt vmcnt(52)
	ds_write_b64 v247, v[12:13] offset:13056
	ds_write_b64 v247, v[14:15] offset:13072
	s_waitcnt vmcnt(51)
	ds_write_b64 v247, v[16:17] offset:17408
	ds_write_b64 v247, v[18:19] offset:17424
	s_waitcnt vmcnt(50)
	ds_write_b64 v247, v[20:21] offset:21760
	ds_write_b64 v247, v[22:23] offset:21776
	s_waitcnt vmcnt(49)
	ds_write_b64 v247, v[24:25] offset:26112
	ds_write_b64 v247, v[26:27] offset:26128
	s_waitcnt vmcnt(48)
	ds_write_b64 v247, v[28:29] offset:30464
	ds_write_b64 v247, v[30:31] offset:30480
	s_waitcnt vmcnt(47)
	ds_write_b64 v249, v[32:33] offset:34816
	ds_write_b64 v249, v[34:35] offset:34832
	s_waitcnt vmcnt(46)
	ds_write_b64 v249, v[36:37] offset:39424
	ds_write_b64 v249, v[38:39] offset:39440
	s_waitcnt vmcnt(45)
	ds_write_b64 v249, v[40:41] offset:44032
	ds_write_b64 v249, v[42:43] offset:44048
	s_waitcnt vmcnt(44)
	ds_write_b64 v249, v[44:45] offset:48640
	ds_write_b64 v249, v[46:47] offset:48656
	s_waitcnt vmcnt(43)
	ds_write_b64 v249, v[48:49] offset:53248
	ds_write_b64 v249, v[50:51] offset:53264
	s_waitcnt vmcnt(42)
	ds_write_b64 v249, v[52:53] offset:57856
	ds_write_b64 v249, v[54:55] offset:57872
	s_waitcnt lgkmcnt(0)
	s_barrier
; #define LBAR() do { asm volatile("s_waitcnt lgkmcnt(0)" ::: "memory"); __builtin_amdgcn_s_barrier(); asm volatile("" ::: "memory"); } while (0)
; __device__ __forceinline__ void scan_bh(LAS unsigned char* lds, const ScanP& P, int b, int h, int half, int tid, int lane, int wave) {
;     ...
; #pragma unroll 1
;         for (int n = 0; n < 32; n += 2) {
;             if (n + 2 < 32) L_LOAD(n + 2, sb);
;             L_STORE(lds + ((n + 1) & 1) * SB_SZ, sa);
;             LBAR();
;             if (n + 3 < 32) L_LOAD(n + 3, sa);
;             if (n + 2 < 32) L_STORE(lds + ((n + 2) & 1) * SB_SZ, sb);
;             LBAR();
;         }
.Lscan_ld:
	global_load_dwordx4 v[0:3], v240, s[14:15] offset:-4096
	global_load_dwordx4 v[4:7], v240, s[14:15]
	global_load_dwordx4 v[8:11], v241, s[14:15] offset:-4096
	global_load_dwordx4 v[12:15], v241, s[14:15]
	global_load_dwordx4 v[16:19], v242, s[14:15] offset:-4096
	global_load_dwordx4 v[20:23], v242, s[14:15]
	global_load_dwordx4 v[24:27], v243, s[14:15] offset:-4096
	global_load_dwordx4 v[28:31], v243, s[14:15]
	global_load_dwordx4 v[32:35], v244, s[14:15] offset:-4096
	global_load_dwordx4 v[36:39], v244, s[14:15]
	global_load_dwordx4 v[40:43], v245, s[14:15] offset:-4096
	global_load_dwordx4 v[44:47], v245, s[14:15]
	global_load_dwordx4 v[48:51], v246, s[14:15] offset:-4096
	global_load_dwordx4 v[52:55], v246, s[14:15]
	s_cmp_lt_u32 s16, 27
	s_cselect_b32 s19, 0xd0000, 0
	s_add_u32 s14, s14, s19
	s_addc_u32 s15, s15, 0
	s_waitcnt vmcnt(55)
	ds_write_b64 v248, v[56:57]
	ds_write_b64 v248, v[58:59] offset:16
	s_waitcnt vmcnt(54)
	ds_write_b64 v248, v[60:61] offset:4352
	ds_write_b64 v248, v[62:63] offset:4368
	s_waitcnt vmcnt(53)
	ds_write_b64 v248, v[64:65] offset:8704
	ds_write_b64 v248, v[66:67] offset:8720
	s_waitcnt vmcnt(52)
	ds_write_b64 v248, v[68:69] offset:13056
	ds_write_b64 v248, v[70:71] offset:13072
	s_waitcnt vmcnt(51)
	ds_write_b64 v248, v[72:73] offset:17408
	ds_write_b64 v248, v[74:75] offset:17424
	s_waitcnt vmcnt(50)
	ds_write_b64 v248, v[76:77] offset:21760
	ds_write_b64 v248, v[78:79] offset:21776
	s_waitcnt vmcnt(49)
	ds_write_b64 v248, v[80:81] offset:26112
	ds_write_b64 v248, v[82:83] offset:26128
	s_waitcnt vmcnt(48)
	ds_write_b64 v248, v[84:85] offset:30464
	ds_write_b64 v248, v[86:87] offset:30480
	s_waitcnt vmcnt(47)
	ds_write_b64 v250, v[88:89] offset:34816
	ds_write_b64 v250, v[90:91] offset:34832
	s_waitcnt vmcnt(46)
	ds_write_b64 v250, v[92:93] offset:39424
	ds_write_b64 v250, v[94:95] offset:39440
	s_waitcnt vmcnt(45)
	ds_write_b64 v250, v[96:97] offset:44032
	ds_write_b64 v250, v[98:99] offset:44048
	s_waitcnt vmcnt(44)
	ds_write_b64 v250, v[100:101] offset:48640
	ds_write_b64 v250, v[102:103] offset:48656
	s_waitcnt vmcnt(43)
	ds_write_b64 v250, v[104:105] offset:53248
	ds_write_b64 v250, v[106:107] offset:53264
	s_waitcnt vmcnt(42)
	ds_write_b64 v250, v[108:109] offset:57856
	ds_write_b64 v250, v[110:111] offset:57872
	s_waitcnt lgkmcnt(0)
	s_barrier
	s_add_i32 s16, s16, 1
	s_cmp_eq_u32 s16, 31
	s_cbranch_scc1 .Lscan_ld_last
	global_load_dwordx4 v[56:59], v240, s[14:15] offset:-4096
	global_load_dwordx4 v[60:63], v240, s[14:15]
	global_load_dwordx4 v[64:67], v241, s[14:15] offset:-4096
	global_load_dwordx4 v[68:71], v241, s[14:15]
	global_load_dwordx4 v[72:75], v242, s[14:15] offset:-4096
	global_load_dwordx4 v[76:79], v242, s[14:15]
	global_load_dwordx4 v[80:83], v243, s[14:15] offset:-4096
	global_load_dwordx4 v[84:87], v243, s[14:15]
	global_load_dwordx4 v[88:91], v244, s[14:15] offset:-4096
	global_load_dwordx4 v[92:95], v244, s[14:15]
	global_load_dwordx4 v[96:99], v245, s[14:15] offset:-4096
	global_load_dwordx4 v[100:103], v245, s[14:15]
	global_load_dwordx4 v[104:107], v246, s[14:15] offset:-4096
	global_load_dwordx4 v[108:111], v246, s[14:15]
	s_cmp_lt_u32 s16, 27
	s_cselect_b32 s19, 0xd0000, 0
	s_add_u32 s14, s14, s19
	s_addc_u32 s15, s15, 0
	s_waitcnt vmcnt(55)
	ds_write_b64 v247, v[112:113]
	ds_write_b64 v247, v[114:115] offset:16
	s_waitcnt vmcnt(54)
	ds_write_b64 v247, v[116:117] offset:4352
	ds_write_b64 v247, v[118:119] offset:4368
	s_waitcnt vmcnt(53)
	ds_write_b64 v247, v[120:121] offset:8704
	ds_write_b64 v247, v[122:123] offset:8720
	s_waitcnt vmcnt(52)
	ds_write_b64 v247, v[124:125] offset:13056
	ds_write_b64 v247, v[126:127] offset:13072
	s_waitcnt vmcnt(51)
	ds_write_b64 v247, v[128:129] offset:17408
	ds_write_b64 v247, v[130:131] offset:17424
	s_waitcnt vmcnt(50)
	ds_write_b64 v247, v[132:133] offset:21760
	ds_write_b64 v247, v[134:135] offset:21776
	s_waitcnt vmcnt(49)
	ds_write_b64 v247, v[136:137] offset:26112
	ds_write_b64 v247, v[138:139] offset:26128
	s_waitcnt vmcnt(48)
	ds_write_b64 v247, v[140:141] offset:30464
	ds_write_b64 v247, v[142:143] offset:30480
	s_waitcnt vmcnt(47)
	ds_write_b64 v249, v[144:145] offset:34816
	ds_write_b64 v249, v[146:147] offset:34832
	s_waitcnt vmcnt(46)
	ds_write_b64 v249, v[148:149] offset:39424
	ds_write_b64 v249, v[150:151] offset:39440
	s_waitcnt vmcnt(45)
	ds_write_b64 v249, v[156:157] offset:44032
	ds_write_b64 v249, v[158:159] offset:44048
	s_waitcnt vmcnt(44)
	ds_write_b64 v249, v[160:161] offset:48640
	ds_write_b64 v249, v[162:163] offset:48656
	s_waitcnt vmcnt(43)
	ds_write_b64 v249, v[164:165] offset:53248
	ds_write_b64 v249, v[166:167] offset:53264
	s_waitcnt vmcnt(42)
	ds_write_b64 v249, v[168:169] offset:57856
	ds_write_b64 v249, v[170:171] offset:57872
	s_waitcnt lgkmcnt(0)
	s_barrier
	s_add_i32 s16, s16, 1
	s_cmp_eq_u32 s16, 31
	s_cbranch_scc1 .Lscan_ld_last
; #define LBAR() do { asm volatile("s_waitcnt lgkmcnt(0)" ::: "memory"); __builtin_amdgcn_s_barrier(); asm volatile("" ::: "memory"); } while (0)
; __device__ __forceinline__ void scan_bh(LAS unsigned char* lds, const ScanP& P, int b, int h, int half, int tid, int lane, int wave) {
;     ...
; #pragma unroll 1
;         for (int n = 0; n < 32; n += 2) {
;             if (n + 2 < 32) L_LOAD(n + 2, sb);
;             L_STORE(lds + ((n + 1) & 1) * SB_SZ, sa);
;             LBAR();
;             if (n + 3 < 32) L_LOAD(n + 3, sa);
;             if (n + 2 < 32) L_STORE(lds + ((n + 2) & 1) * SB_SZ, sb);
;             LBAR();
;         }
	global_load_dwordx4 v[112:115], v240, s[14:15] offset:-4096
	global_load_dwordx4 v[116:119], v240, s[14:15]
	global_load_dwordx4 v[120:123], v241, s[14:15] offset:-4096
	global_load_dwordx4 v[124:127], v241, s[14:15]
	global_load_dwordx4 v[128:131], v242, s[14:15] offset:-4096
	global_load_dwordx4 v[132:135], v242, s[14:15]
	global_load_dwordx4 v[136:139], v243, s[14:15] offset:-4096
	global_load_dwordx4 v[140:143], v243, s[14:15]
	global_load_dwordx4 v[144:147], v244, s[14:15] offset:-4096
	global_load_dwordx4 v[148:151], v244, s[14:15]
	global_load_dwordx4 v[156:159], v245, s[14:15] offset:-4096
	global_load_dwordx4 v[160:163], v245, s[14:15]
	global_load_dwordx4 v[164:167], v246, s[14:15] offset:-4096
	global_load_dwordx4 v[168:171], v246, s[14:15]
	s_cmp_lt_u32 s16, 27
	s_cselect_b32 s19, 0xd0000, 0
	s_add_u32 s14, s14, s19
	s_addc_u32 s15, s15, 0
	s_waitcnt vmcnt(55)
	ds_write_b64 v248, v[172:173]
	ds_write_b64 v248, v[174:175] offset:16
	s_waitcnt vmcnt(54)
	ds_write_b64 v248, v[176:177] offset:4352
	ds_write_b64 v248, v[178:179] offset:4368
	s_waitcnt vmcnt(53)
	ds_write_b64 v248, v[180:181] offset:8704
	ds_write_b64 v248, v[182:183] offset:8720
	s_waitcnt vmcnt(52)
	ds_write_b64 v248, v[184:185] offset:13056
	ds_write_b64 v248, v[186:187] offset:13072
	s_waitcnt vmcnt(51)
	ds_write_b64 v248, v[188:189] offset:17408
	ds_write_b64 v248, v[190:191] offset:17424
	s_waitcnt vmcnt(50)
	ds_write_b64 v248, v[200:201] offset:21760
	ds_write_b64 v248, v[202:203] offset:21776
	s_waitcnt vmcnt(49)
	ds_write_b64 v248, v[204:205] offset:26112
	ds_write_b64 v248, v[206:207] offset:26128
	s_waitcnt vmcnt(48)
	ds_write_b64 v248, v[208:209] offset:30464
	ds_write_b64 v248, v[210:211] offset:30480
	s_waitcnt vmcnt(47)
	ds_write_b64 v250, v[212:213] offset:34816
	ds_write_b64 v250, v[214:215] offset:34832
	s_waitcnt vmcnt(46)
	ds_write_b64 v250, v[216:217] offset:39424
	ds_write_b64 v250, v[218:219] offset:39440
	s_waitcnt vmcnt(45)
	ds_write_b64 v250, v[220:221] offset:44032
	ds_write_b64 v250, v[222:223] offset:44048
	s_waitcnt vmcnt(44)
	ds_write_b64 v250, v[224:225] offset:48640
	ds_write_b64 v250, v[226:227] offset:48656
	s_waitcnt vmcnt(43)
	ds_write_b64 v250, v[228:229] offset:53248
	ds_write_b64 v250, v[230:231] offset:53264
	s_waitcnt vmcnt(42)
	ds_write_b64 v250, v[232:233] offset:57856
	ds_write_b64 v250, v[234:235] offset:57872
	s_waitcnt lgkmcnt(0)
	s_barrier
	s_add_i32 s16, s16, 1
	s_cmp_eq_u32 s16, 31
	s_cbranch_scc1 .Lscan_ld_last
	global_load_dwordx4 v[172:175], v240, s[14:15] offset:-4096
	global_load_dwordx4 v[176:179], v240, s[14:15]
	global_load_dwordx4 v[180:183], v241, s[14:15] offset:-4096
	global_load_dwordx4 v[184:187], v241, s[14:15]
	global_load_dwordx4 v[188:191], v242, s[14:15] offset:-4096
	global_load_dwordx4 v[200:203], v242, s[14:15]
	global_load_dwordx4 v[204:207], v243, s[14:15] offset:-4096
	global_load_dwordx4 v[208:211], v243, s[14:15]
	global_load_dwordx4 v[212:215], v244, s[14:15] offset:-4096
	global_load_dwordx4 v[216:219], v244, s[14:15]
	global_load_dwordx4 v[220:223], v245, s[14:15] offset:-4096
	global_load_dwordx4 v[224:227], v245, s[14:15]
	global_load_dwordx4 v[228:231], v246, s[14:15] offset:-4096
	global_load_dwordx4 v[232:235], v246, s[14:15]
	s_cmp_lt_u32 s16, 27
	s_cselect_b32 s19, 0xd0000, 0
	s_add_u32 s14, s14, s19
	s_addc_u32 s15, s15, 0
	s_waitcnt vmcnt(55)
	ds_write_b64 v247, v[0:1]
	ds_write_b64 v247, v[2:3] offset:16
	s_waitcnt vmcnt(54)
	ds_write_b64 v247, v[4:5] offset:4352
	ds_write_b64 v247, v[6:7] offset:4368
	s_waitcnt vmcnt(53)
	ds_write_b64 v247, v[8:9] offset:8704
	ds_write_b64 v247, v[10:11] offset:8720
	s_waitcnt vmcnt(52)
	ds_write_b64 v247, v[12:13] offset:13056
	ds_write_b64 v247, v[14:15] offset:13072
	s_waitcnt vmcnt(51)
	ds_write_b64 v247, v[16:17] offset:17408
	ds_write_b64 v247, v[18:19] offset:17424
	s_waitcnt vmcnt(50)
	ds_write_b64 v247, v[20:21] offset:21760
	ds_write_b64 v247, v[22:23] offset:21776
	s_waitcnt vmcnt(49)
	ds_write_b64 v247, v[24:25] offset:26112
	ds_write_b64 v247, v[26:27] offset:26128
	s_waitcnt vmcnt(48)
	ds_write_b64 v247, v[28:29] offset:30464
	ds_write_b64 v247, v[30:31] offset:30480
	s_waitcnt vmcnt(47)
	ds_write_b64 v249, v[32:33] offset:34816
	ds_write_b64 v249, v[34:35] offset:34832
	s_waitcnt vmcnt(46)
	ds_write_b64 v249, v[36:37] offset:39424
	ds_write_b64 v249, v[38:39] offset:39440
	s_waitcnt vmcnt(45)
	ds_write_b64 v249, v[40:41] offset:44032
	ds_write_b64 v249, v[42:43] offset:44048
	s_waitcnt vmcnt(44)
	ds_write_b64 v249, v[44:45] offset:48640
	ds_write_b64 v249, v[46:47] offset:48656
	s_waitcnt vmcnt(43)
	ds_write_b64 v249, v[48:49] offset:53248
	ds_write_b64 v249, v[50:51] offset:53264
	s_waitcnt vmcnt(42)
	ds_write_b64 v249, v[52:53] offset:57856
	ds_write_b64 v249, v[54:55] offset:57872
	s_waitcnt lgkmcnt(0)
	s_barrier
	s_add_i32 s16, s16, 1
	s_cmp_eq_u32 s16, 31
	s_cbranch_scc1 .Lscan_ld_last
	s_branch .Lscan_ld
